# P1 epilogue: column-scale (cmax) loads issued before the row-scale wait so both latencies overlap
# speedup vs baseline: 1.0084x; 1.0084x over previous
.LBB0_634:
	v_cvt_f32_i32_e32 v124, v124
	v_cvt_f32_i32_e32 v125, v125
	v_cvt_f32_i32_e32 v162, v126
	v_cvt_f32_i32_e32 v163, v127
	v_cvt_f32_i32_e32 v92, v92
	v_cvt_f32_i32_e32 v93, v93
	v_cvt_f32_i32_e32 v160, v94
	v_cvt_f32_i32_e32 v161, v95
	v_cvt_f32_i32_e32 v120, v120
	v_cvt_f32_i32_e32 v121, v121
	v_cvt_f32_i32_e32 v94, v122
	v_cvt_f32_i32_e32 v95, v123
	v_cvt_f32_i32_e32 v88, v88
	v_cvt_f32_i32_e32 v89, v89
	v_cvt_f32_i32_e32 v122, v90
	v_cvt_f32_i32_e32 v123, v91
	v_cvt_f32_i32_e32 v116, v116
	v_cvt_f32_i32_e32 v117, v117
	v_cvt_f32_i32_e32 v90, v118
	v_cvt_f32_i32_e32 v91, v119
	v_cvt_f32_i32_e32 v84, v84
	v_cvt_f32_i32_e32 v85, v85
	v_cvt_f32_i32_e32 v164, v86
	v_cvt_f32_i32_e32 v165, v87
	v_cvt_f32_i32_e32 v112, v112
	v_cvt_f32_i32_e32 v113, v113
	v_cvt_f32_i32_e32 v114, v114
	v_cvt_f32_i32_e32 v115, v115
	v_cvt_f32_i32_e32 v80, v80
	v_cvt_f32_i32_e32 v81, v81
	v_cvt_f32_i32_e32 v82, v82
	v_cvt_f32_i32_e32 v83, v83
	v_cvt_f32_i32_e32 v60, v60
	v_cvt_f32_i32_e32 v61, v61
	v_cvt_f32_i32_e32 v168, v62
	v_cvt_f32_i32_e32 v169, v63
	v_cvt_f32_i32_e32 v28, v28
	v_cvt_f32_i32_e32 v29, v29
	v_cvt_f32_i32_e32 v166, v30
	v_cvt_f32_i32_e32 v167, v31
	v_cvt_f32_i32_e32 v56, v56
	v_cvt_f32_i32_e32 v57, v57
	v_cvt_f32_i32_e32 v172, v58
	v_cvt_f32_i32_e32 v173, v59
	v_cvt_f32_i32_e32 v24, v24
	v_cvt_f32_i32_e32 v25, v25
	v_cvt_f32_i32_e32 v170, v26
	v_cvt_f32_i32_e32 v171, v27
	v_cvt_f32_i32_e32 v52, v52
	v_cvt_f32_i32_e32 v53, v53
	v_cvt_f32_i32_e32 v26, v54
	v_cvt_f32_i32_e32 v27, v55
	v_cvt_f32_i32_e32 v20, v20
	v_cvt_f32_i32_e32 v21, v21
	v_cvt_f32_i32_e32 v174, v22
	v_cvt_f32_i32_e32 v175, v23
	v_cvt_f32_i32_e32 v48, v48
	v_cvt_f32_i32_e32 v49, v49
	v_cvt_f32_i32_e32 v178, v50
	v_cvt_f32_i32_e32 v179, v51
	v_cvt_f32_i32_e32 v16, v16
	v_cvt_f32_i32_e32 v17, v17
	v_cvt_f32_i32_e32 v176, v18
	v_cvt_f32_i32_e32 v177, v19
	v_cvt_f32_i32_e32 v108, v108
	v_cvt_f32_i32_e32 v109, v109
	v_cvt_f32_i32_e32 v22, v110
	v_cvt_f32_i32_e32 v23, v111
	v_cvt_f32_i32_e32 v76, v76
	v_cvt_f32_i32_e32 v77, v77
	v_cvt_f32_i32_e32 v18, v78
	v_cvt_f32_i32_e32 v19, v79
	v_cvt_f32_i32_e32 v104, v104
	v_cvt_f32_i32_e32 v105, v105
	v_cvt_f32_i32_e32 v30, v106
	v_cvt_f32_i32_e32 v31, v107
	v_cvt_f32_i32_e32 v72, v72
	v_cvt_f32_i32_e32 v73, v73
	v_cvt_f32_i32_e32 v50, v74
	v_cvt_f32_i32_e32 v51, v75
	v_cvt_f32_i32_e32 v100, v100
	v_cvt_f32_i32_e32 v101, v101
	v_cvt_f32_i32_e32 v54, v102
	v_cvt_f32_i32_e32 v55, v103
	v_cvt_f32_i32_e32 v68, v68
	v_cvt_f32_i32_e32 v69, v69
	v_cvt_f32_i32_e32 v180, v70
	v_cvt_f32_i32_e32 v181, v71
	v_cvt_f32_i32_e32 v96, v96
	v_cvt_f32_i32_e32 v97, v97
	v_cvt_f32_i32_e32 v70, v98
	v_cvt_f32_i32_e32 v71, v99
	v_cvt_f32_i32_e32 v64, v64
	v_cvt_f32_i32_e32 v65, v65
	v_cvt_f32_i32_e32 v186, v66
	v_cvt_f32_i32_e32 v187, v67
	v_cvt_f32_i32_e32 v44, v44
	v_cvt_f32_i32_e32 v45, v45
	v_cvt_f32_i32_e32 v184, v46
	v_cvt_f32_i32_e32 v185, v47
	v_cvt_f32_i32_e32 v12, v12
	v_cvt_f32_i32_e32 v13, v13
	v_cvt_f32_i32_e32 v182, v14
	v_cvt_f32_i32_e32 v183, v15
	v_cvt_f32_i32_e32 v40, v40
	v_cvt_f32_i32_e32 v41, v41
	v_cvt_f32_i32_e32 v190, v42
	v_cvt_f32_i32_e32 v191, v43
	v_cvt_f32_i32_e32 v8, v8
	v_cvt_f32_i32_e32 v9, v9
	v_cvt_f32_i32_e32 v188, v10
	v_cvt_f32_i32_e32 v189, v11
	v_cvt_f32_i32_e32 v36, v36
	v_cvt_f32_i32_e32 v37, v37
	v_cvt_f32_i32_e32 v194, v38
	v_cvt_f32_i32_e32 v195, v39
	v_cvt_f32_i32_e32 v4, v4
	v_cvt_f32_i32_e32 v5, v5
	v_cvt_f32_i32_e32 v192, v6
	v_cvt_f32_i32_e32 v193, v7
	v_cvt_f32_i32_e32 v32, v32
	v_cvt_f32_i32_e32 v33, v33
	v_cvt_f32_i32_e32 v198, v34
	v_cvt_f32_i32_e32 v199, v35
	v_cvt_f32_i32_e32 v0, v0
	v_cvt_f32_i32_e32 v1, v1
	v_cvt_f32_i32_e32 v196, v2
	v_cvt_f32_i32_e32 v197, v3
	s_lshl_b32 s56, s60, 8
	s_ashr_i32 s57, s56, 31
	v_lshl_add_u64 v[6:7], s[56:57], 2, v[146:147]
	global_load_dwordx4 v[130:133], v[6:7], off
	global_load_dwordx4 v[126:129], v[6:7], off offset:16
	global_load_dwordx4 v[206:209], v[6:7], off offset:512
	global_load_dwordx4 v[210:213], v[6:7], off offset:528
	s_lshl_b32 s29, s0, 8
	s_add_i32 s29, s29, s67
	s_andn2_b64 vcc, exec, s[24:25]
	v_or_b32_e32 v2, s29, v145
	s_cbranch_vccnz .LBB0_636
	v_ashrrev_i32_e32 v3, 31, v2
	v_lshl_add_u64 v[6:7], v[2:3], 2, s[40:41]
	global_load_dword v10, v[6:7], off
	global_load_dword v14, v[6:7], off offset:64
	global_load_dword v34, v[6:7], off offset:128
	global_load_dword v38, v[6:7], off offset:192
	global_load_dword v42, v[6:7], off offset:512
	global_load_dword v46, v[6:7], off offset:576
	global_load_dword v58, v[6:7], off offset:640
	s_nop 0
	global_load_dword v6, v[6:7], off offset:704
	s_waitcnt vmcnt(0)
	v_pk_mul_f32 v[162:163], v[162:163], v[10:11] op_sel_hi:[1,0]
	v_pk_mul_f32 v[124:125], v[124:125], v[10:11] op_sel_hi:[1,0]
	v_pk_mul_f32 v[160:161], v[160:161], v[10:11] op_sel_hi:[1,0]
	v_pk_mul_f32 v[92:93], v[92:93], v[10:11] op_sel_hi:[1,0]
	v_pk_mul_f32 v[168:169], v[168:169], v[10:11] op_sel_hi:[1,0]
	v_pk_mul_f32 v[60:61], v[60:61], v[10:11] op_sel_hi:[1,0]
	v_pk_mul_f32 v[166:167], v[166:167], v[10:11] op_sel_hi:[1,0]
	v_pk_mul_f32 v[28:29], v[28:29], v[10:11] op_sel_hi:[1,0]
	v_pk_mul_f32 v[94:95], v[94:95], v[14:15] op_sel_hi:[1,0]
	v_pk_mul_f32 v[120:121], v[120:121], v[14:15] op_sel_hi:[1,0]
	v_pk_mul_f32 v[122:123], v[122:123], v[14:15] op_sel_hi:[1,0]
	v_pk_mul_f32 v[88:89], v[88:89], v[14:15] op_sel_hi:[1,0]
	v_pk_mul_f32 v[172:173], v[172:173], v[14:15] op_sel_hi:[1,0]
	v_pk_mul_f32 v[56:57], v[56:57], v[14:15] op_sel_hi:[1,0]
	v_pk_mul_f32 v[170:171], v[170:171], v[14:15] op_sel_hi:[1,0]
	v_pk_mul_f32 v[24:25], v[24:25], v[14:15] op_sel_hi:[1,0]
	v_pk_mul_f32 v[90:91], v[90:91], v[34:35] op_sel_hi:[1,0]
	v_pk_mul_f32 v[116:117], v[116:117], v[34:35] op_sel_hi:[1,0]
	v_pk_mul_f32 v[164:165], v[164:165], v[34:35] op_sel_hi:[1,0]
	v_pk_mul_f32 v[84:85], v[84:85], v[34:35] op_sel_hi:[1,0]
	v_pk_mul_f32 v[26:27], v[26:27], v[34:35] op_sel_hi:[1,0]
	v_pk_mul_f32 v[52:53], v[52:53], v[34:35] op_sel_hi:[1,0]
	v_pk_mul_f32 v[174:175], v[174:175], v[34:35] op_sel_hi:[1,0]
	v_pk_mul_f32 v[20:21], v[20:21], v[34:35] op_sel_hi:[1,0]
	v_pk_mul_f32 v[114:115], v[114:115], v[38:39] op_sel_hi:[1,0]
	v_pk_mul_f32 v[112:113], v[112:113], v[38:39] op_sel_hi:[1,0]
	v_pk_mul_f32 v[82:83], v[82:83], v[38:39] op_sel_hi:[1,0]
	v_pk_mul_f32 v[80:81], v[80:81], v[38:39] op_sel_hi:[1,0]
	v_pk_mul_f32 v[178:179], v[178:179], v[38:39] op_sel_hi:[1,0]
	v_pk_mul_f32 v[48:49], v[48:49], v[38:39] op_sel_hi:[1,0]
	v_pk_mul_f32 v[176:177], v[176:177], v[38:39] op_sel_hi:[1,0]
	v_pk_mul_f32 v[16:17], v[16:17], v[38:39] op_sel_hi:[1,0]
	v_pk_mul_f32 v[22:23], v[22:23], v[42:43] op_sel_hi:[1,0]
	v_pk_mul_f32 v[108:109], v[108:109], v[42:43] op_sel_hi:[1,0]
	v_pk_mul_f32 v[18:19], v[18:19], v[42:43] op_sel_hi:[1,0]
	v_pk_mul_f32 v[76:77], v[76:77], v[42:43] op_sel_hi:[1,0]
	v_pk_mul_f32 v[184:185], v[184:185], v[42:43] op_sel_hi:[1,0]
	v_pk_mul_f32 v[44:45], v[44:45], v[42:43] op_sel_hi:[1,0]
	v_pk_mul_f32 v[182:183], v[182:183], v[42:43] op_sel_hi:[1,0]
	v_pk_mul_f32 v[12:13], v[12:13], v[42:43] op_sel_hi:[1,0]
	v_pk_mul_f32 v[30:31], v[30:31], v[46:47] op_sel_hi:[1,0]
	v_pk_mul_f32 v[104:105], v[104:105], v[46:47] op_sel_hi:[1,0]
	v_pk_mul_f32 v[50:51], v[50:51], v[46:47] op_sel_hi:[1,0]
	v_pk_mul_f32 v[72:73], v[72:73], v[46:47] op_sel_hi:[1,0]
	v_pk_mul_f32 v[190:191], v[190:191], v[46:47] op_sel_hi:[1,0]
	v_pk_mul_f32 v[40:41], v[40:41], v[46:47] op_sel_hi:[1,0]
	v_pk_mul_f32 v[188:189], v[188:189], v[46:47] op_sel_hi:[1,0]
	v_pk_mul_f32 v[8:9], v[8:9], v[46:47] op_sel_hi:[1,0]
	v_pk_mul_f32 v[54:55], v[54:55], v[58:59] op_sel_hi:[1,0]
	v_pk_mul_f32 v[100:101], v[100:101], v[58:59] op_sel_hi:[1,0]
	v_pk_mul_f32 v[180:181], v[180:181], v[58:59] op_sel_hi:[1,0]
	v_pk_mul_f32 v[68:69], v[68:69], v[58:59] op_sel_hi:[1,0]
	v_pk_mul_f32 v[194:195], v[194:195], v[58:59] op_sel_hi:[1,0]
	v_pk_mul_f32 v[36:37], v[36:37], v[58:59] op_sel_hi:[1,0]
	v_pk_mul_f32 v[192:193], v[192:193], v[58:59] op_sel_hi:[1,0]
	v_pk_mul_f32 v[4:5], v[4:5], v[58:59] op_sel_hi:[1,0]
	v_pk_mul_f32 v[70:71], v[70:71], v[6:7] op_sel_hi:[1,0]
	v_pk_mul_f32 v[96:97], v[96:97], v[6:7] op_sel_hi:[1,0]
	v_pk_mul_f32 v[186:187], v[186:187], v[6:7] op_sel_hi:[1,0]
	v_pk_mul_f32 v[64:65], v[64:65], v[6:7] op_sel_hi:[1,0]
	v_pk_mul_f32 v[198:199], v[198:199], v[6:7] op_sel_hi:[1,0]
	v_pk_mul_f32 v[32:33], v[32:33], v[6:7] op_sel_hi:[1,0]
	v_pk_mul_f32 v[196:197], v[196:197], v[6:7] op_sel_hi:[1,0]
	v_pk_mul_f32 v[0:1], v[0:1], v[6:7] op_sel_hi:[1,0]
.LBB0_636:
	s_cmp_lt_i32 s60, 16
	s_cselect_b64 s[58:59], -1, 0
	s_sub_i32 s0, s60, 28
	s_cmp_lt_u32 s0, 48
	s_cselect_b64 s[8:9], -1, 0
	s_or_b64 s[8:9], s[58:59], s[8:9]
	s_andn2_b64 vcc, exec, s[8:9]
	s_mov_b64 s[8:9], -1
	s_waitcnt vmcnt(0)
	v_pk_mul_f32 v[6:7], v[132:133], s[26:27] op_sel_hi:[1,0]
	v_pk_mul_f32 v[10:11], v[130:131], s[26:27] op_sel_hi:[1,0]
	v_pk_mul_f32 v[14:15], v[128:129], s[26:27] op_sel_hi:[1,0]
	v_pk_mul_f32 v[126:127], v[126:127], s[26:27] op_sel_hi:[1,0]
	v_pk_mul_f32 v[128:129], v[208:209], s[26:27] op_sel_hi:[1,0]
	v_pk_mul_f32 v[130:131], v[206:207], s[26:27] op_sel_hi:[1,0]
	v_pk_mul_f32 v[132:133], v[212:213], s[26:27] op_sel_hi:[1,0]
	v_pk_mul_f32 v[206:207], v[210:211], s[26:27] op_sel_hi:[1,0]
	v_pk_mul_f32 v[106:107], v[162:163], v[6:7]
	v_pk_mul_f32 v[110:111], v[124:125], v[10:11]
	v_pk_mul_f32 v[94:95], v[94:95], v[6:7]
	v_pk_mul_f32 v[98:99], v[120:121], v[10:11]
	v_pk_mul_f32 v[86:87], v[90:91], v[6:7]
	v_pk_mul_f32 v[90:91], v[116:117], v[10:11]
	v_pk_mul_f32 v[74:75], v[114:115], v[6:7]
	v_pk_mul_f32 v[78:79], v[112:113], v[10:11]
	v_pk_mul_f32 v[58:59], v[22:23], v[6:7]
	v_pk_mul_f32 v[62:63], v[108:109], v[10:11]
	v_pk_mul_f32 v[42:43], v[30:31], v[6:7]
	v_pk_mul_f32 v[46:47], v[104:105], v[10:11]
	v_pk_mul_f32 v[22:23], v[54:55], v[6:7]
	v_pk_mul_f32 v[30:31], v[100:101], v[10:11]
	v_pk_mul_f32 v[6:7], v[70:71], v[6:7]
	v_pk_mul_f32 v[10:11], v[96:97], v[10:11]
	v_pk_mul_f32 v[114:115], v[160:161], v[14:15]
	v_pk_mul_f32 v[118:119], v[92:93], v[126:127]
	v_pk_mul_f32 v[96:97], v[122:123], v[14:15]
	v_pk_mul_f32 v[102:103], v[88:89], v[126:127]
	v_pk_mul_f32 v[88:89], v[164:165], v[14:15]
	v_pk_mul_f32 v[84:85], v[84:85], v[126:127]
	v_pk_mul_f32 v[82:83], v[82:83], v[14:15]
	v_pk_mul_f32 v[80:81], v[80:81], v[126:127]
	v_pk_mul_f32 v[66:67], v[18:19], v[14:15]
	v_pk_mul_f32 v[70:71], v[76:77], v[126:127]
	v_pk_mul_f32 v[50:51], v[50:51], v[14:15]
	v_pk_mul_f32 v[54:55], v[72:73], v[126:127]
	v_pk_mul_f32 v[34:35], v[180:181], v[14:15]
	v_pk_mul_f32 v[38:39], v[68:69], v[126:127]
	v_pk_mul_f32 v[14:15], v[186:187], v[14:15]
	v_pk_mul_f32 v[18:19], v[64:65], v[126:127]
	v_pk_mul_f32 v[122:123], v[168:169], v[128:129]
	v_pk_mul_f32 v[124:125], v[60:61], v[130:131]
	v_pk_mul_f32 v[108:109], v[172:173], v[128:129]
	v_pk_mul_f32 v[112:113], v[56:57], v[130:131]
	v_pk_mul_f32 v[76:77], v[26:27], v[128:129]
	v_pk_mul_f32 v[92:93], v[52:53], v[130:131]
	v_pk_mul_f32 v[60:61], v[178:179], v[128:129]
	v_pk_mul_f32 v[64:65], v[48:49], v[130:131]
	v_pk_mul_f32 v[52:53], v[184:185], v[128:129]
	v_pk_mul_f32 v[56:57], v[44:45], v[130:131]
	v_pk_mul_f32 v[44:45], v[190:191], v[128:129]
	v_pk_mul_f32 v[48:49], v[40:41], v[130:131]
	v_pk_mul_f32 v[40:41], v[194:195], v[128:129]
	v_pk_mul_f32 v[36:37], v[36:37], v[130:131]
	v_pk_mul_f32 v[26:27], v[198:199], v[128:129]
	v_pk_mul_f32 v[32:33], v[32:33], v[130:131]
	v_pk_mul_f32 v[126:127], v[166:167], v[132:133]
	v_pk_mul_f32 v[128:129], v[28:29], v[206:207]
	v_pk_mul_f32 v[116:117], v[170:171], v[132:133]
	v_pk_mul_f32 v[120:121], v[24:25], v[206:207]
	v_pk_mul_f32 v[100:101], v[174:175], v[132:133]
	v_pk_mul_f32 v[104:105], v[20:21], v[206:207]
	v_pk_mul_f32 v[68:69], v[176:177], v[132:133]
	v_pk_mul_f32 v[72:73], v[16:17], v[206:207]
	v_pk_mul_f32 v[24:25], v[182:183], v[132:133]
	v_pk_mul_f32 v[28:29], v[12:13], v[206:207]
	v_pk_mul_f32 v[16:17], v[188:189], v[132:133]
	v_pk_mul_f32 v[20:21], v[8:9], v[206:207]
	v_pk_mul_f32 v[8:9], v[192:193], v[132:133]
	v_pk_mul_f32 v[12:13], v[4:5], v[206:207]
	v_pk_mul_f32 v[4:5], v[196:197], v[132:133]
	v_pk_mul_f32 v[0:1], v[0:1], v[206:207]
	s_cbranch_vccz .LBB0_764
	s_cmp_lt_u32 s60, 28
	s_cbranch_scc1 .LBB0_641
	s_and_b64 vcc, exec, s[20:21]
	s_cbranch_vccz .LBB0_640
	v_mul_f32_e32 v3, 0xbfb8aa3b, v110
	v_exp_f32_e32 v130, v3
	v_mul_f32_e32 v3, 0xbfb8aa3b, v111
	v_exp_f32_e32 v131, v3
	v_mul_f32_e32 v132, 0xbfb8aa3b, v118
	v_exp_f32_e32 v132, v132
	v_mad_i64_i32 v[164:165], s[8:9], v2, s82, v[148:149]
	v_pk_add_f32 v[130:131], v[130:131], 1.0 op_sel_hi:[1,0]
	s_nop 0
	s_nop 0
	v_mul_f32_e32 v133, 0xbfb8aa3b, v119
	v_rcp_f32_e32 v3, v131
	s_nop 0
	v_mul_f32_e32 v131, 1.0, v3
	v_exp_f32_e32 v133, v133
	s_nop 0
	v_pk_add_f32 v[132:133], v[132:133], 1.0 op_sel_hi:[1,0]
	v_rcp_f32_e32 v3, v130
	s_nop 0
	v_mul_f32_e32 v130, 1.0, v3
	v_rcp_f32_e32 v3, v133
	s_nop 0
	v_mul_f32_e32 v161, 1.0, v3
	v_mul_f32_e32 v160, 0xbfb8aa3b, v106
	v_exp_f32_e32 v162, v160
	v_mul_f32_e32 v160, 0xbfb8aa3b, v107
	v_exp_f32_e32 v163, v160
	v_rcp_f32_e32 v3, v132
	s_nop 0
	v_mul_f32_e32 v160, 1.0, v3
	v_pk_add_f32 v[162:163], v[162:163], 1.0 op_sel_hi:[1,0]
	v_mul_f32_e32 v3, 0xbfb8aa3b, v114
	v_exp_f32_e32 v166, v3
	v_mul_f32_e32 v142, 0xbfb8aa3b, v115
	v_exp_f32_e32 v167, v142
	v_rcp_f32_e32 v3, v163
	s_nop 0
	v_mul_f32_e32 v133, 1.0, v3
	v_pk_add_f32 v[166:167], v[166:167], 1.0 op_sel_hi:[1,0]
	v_rcp_f32_e32 v3, v162
	s_nop 0
	v_mul_f32_e32 v132, 1.0, v3
	global_store_dwordx4 v[164:165], v[130:133], off
	s_nop 1
	v_rcp_f32_e32 v3, v167
	s_nop 0
	v_mul_f32_e32 v163, 1.0, v3
	v_mul_f32_e32 v130, 0xbfb8aa3b, v98
	v_mul_f32_e32 v131, 0xbfb8aa3b, v99
	v_exp_f32_e32 v130, v130
	v_exp_f32_e32 v131, v131
	v_rcp_f32_e32 v3, v166
	s_nop 0
	v_mul_f32_e32 v162, 1.0, v3
	v_or_b32_e32 v3, 16, v2
	global_store_dwordx4 v[164:165], v[160:163], off offset:16
	v_pk_add_f32 v[130:131], v[130:131], 1.0 op_sel_hi:[1,0]
	v_mad_i64_i32 v[164:165], s[8:9], v3, s82, v[148:149]
	v_mul_f32_e32 v3, 0xbfb8aa3b, v102
	v_exp_f32_e32 v132, v3
	v_mul_f32_e32 v133, 0xbfb8aa3b, v103
	v_exp_f32_e32 v133, v133
	v_rcp_f32_e32 v3, v131
	s_nop 0
	v_mul_f32_e32 v131, 1.0, v3
	v_pk_add_f32 v[132:133], v[132:133], 1.0 op_sel_hi:[1,0]
	v_rcp_f32_e32 v3, v130
	s_nop 0
	v_mul_f32_e32 v130, 1.0, v3
	v_rcp_f32_e32 v3, v133
	s_nop 0
	v_mul_f32_e32 v161, 1.0, v3
	v_mul_f32_e32 v142, 0xbfb8aa3b, v94
	v_exp_f32_e32 v162, v142
	v_mul_f32_e32 v142, 0xbfb8aa3b, v95
	v_exp_f32_e32 v163, v142
	v_rcp_f32_e32 v3, v132
	s_nop 0
	v_mul_f32_e32 v160, 1.0, v3
	v_pk_add_f32 v[162:163], v[162:163], 1.0 op_sel_hi:[1,0]
	v_mul_f32_e32 v3, 0xbfb8aa3b, v96
	v_exp_f32_e32 v166, v3
	v_mul_f32_e32 v142, 0xbfb8aa3b, v97
	v_exp_f32_e32 v167, v142
	v_rcp_f32_e32 v3, v163
	s_nop 0
	v_mul_f32_e32 v133, 1.0, v3
	v_pk_add_f32 v[166:167], v[166:167], 1.0 op_sel_hi:[1,0]
	v_rcp_f32_e32 v3, v162
	s_nop 0
	v_mul_f32_e32 v132, 1.0, v3
	global_store_dwordx4 v[164:165], v[130:133], off
	s_nop 1
	v_rcp_f32_e32 v3, v167
	s_nop 0
	v_mul_f32_e32 v163, 1.0, v3
	v_mul_f32_e32 v130, 0xbfb8aa3b, v90
	v_mul_f32_e32 v131, 0xbfb8aa3b, v91
	v_exp_f32_e32 v130, v130
	v_exp_f32_e32 v131, v131
	v_rcp_f32_e32 v3, v166
	s_nop 0
	v_mul_f32_e32 v162, 1.0, v3
	v_or_b32_e32 v3, 32, v2
	global_store_dwordx4 v[164:165], v[160:163], off offset:16
	v_pk_add_f32 v[130:131], v[130:131], 1.0 op_sel_hi:[1,0]
	v_mad_i64_i32 v[164:165], s[8:9], v3, s82, v[148:149]
	v_mul_f32_e32 v3, 0xbfb8aa3b, v84
	v_exp_f32_e32 v132, v3
	v_mul_f32_e32 v133, 0xbfb8aa3b, v85
	v_exp_f32_e32 v133, v133
	v_rcp_f32_e32 v3, v131
	s_nop 0
	v_mul_f32_e32 v131, 1.0, v3
	v_pk_add_f32 v[132:133], v[132:133], 1.0 op_sel_hi:[1,0]
	v_rcp_f32_e32 v3, v130
	s_nop 0
	v_mul_f32_e32 v130, 1.0, v3
	v_rcp_f32_e32 v3, v133
	s_nop 0
	v_mul_f32_e32 v161, 1.0, v3
	v_mul_f32_e32 v142, 0xbfb8aa3b, v86
	v_exp_f32_e32 v162, v142
	v_mul_f32_e32 v142, 0xbfb8aa3b, v87
	v_exp_f32_e32 v163, v142
	v_rcp_f32_e32 v3, v132
	s_nop 0
	v_mul_f32_e32 v160, 1.0, v3
	v_pk_add_f32 v[162:163], v[162:163], 1.0 op_sel_hi:[1,0]
	v_mul_f32_e32 v3, 0xbfb8aa3b, v88
	v_exp_f32_e32 v166, v3
	v_mul_f32_e32 v142, 0xbfb8aa3b, v89
	v_exp_f32_e32 v167, v142
	v_rcp_f32_e32 v3, v163
	s_nop 0
	v_mul_f32_e32 v133, 1.0, v3
	v_pk_add_f32 v[166:167], v[166:167], 1.0 op_sel_hi:[1,0]
	v_rcp_f32_e32 v3, v162
	s_nop 0
	v_mul_f32_e32 v132, 1.0, v3
	global_store_dwordx4 v[164:165], v[130:133], off
	s_nop 1
	v_rcp_f32_e32 v3, v167
	s_nop 0
	v_mul_f32_e32 v163, 1.0, v3
	v_mul_f32_e32 v130, 0xbfb8aa3b, v78
	v_mul_f32_e32 v131, 0xbfb8aa3b, v79
	v_exp_f32_e32 v130, v130
	v_exp_f32_e32 v131, v131
	v_rcp_f32_e32 v3, v166
	s_nop 0
	v_mul_f32_e32 v162, 1.0, v3
	v_or_b32_e32 v3, 48, v2
	global_store_dwordx4 v[164:165], v[160:163], off offset:16
	v_pk_add_f32 v[130:131], v[130:131], 1.0 op_sel_hi:[1,0]
	v_mad_i64_i32 v[164:165], s[8:9], v3, s82, v[148:149]
	v_mul_f32_e32 v3, 0xbfb8aa3b, v80
	v_exp_f32_e32 v132, v3
	v_mul_f32_e32 v133, 0xbfb8aa3b, v81
	v_exp_f32_e32 v133, v133
	v_rcp_f32_e32 v3, v131
	s_nop 0
	v_mul_f32_e32 v131, 1.0, v3
	v_pk_add_f32 v[132:133], v[132:133], 1.0 op_sel_hi:[1,0]
	v_rcp_f32_e32 v3, v130
	s_nop 0
	v_mul_f32_e32 v130, 1.0, v3
	v_rcp_f32_e32 v3, v133
	s_nop 0
	v_mul_f32_e32 v161, 1.0, v3
	v_mul_f32_e32 v142, 0xbfb8aa3b, v74
	v_exp_f32_e32 v162, v142
	v_mul_f32_e32 v142, 0xbfb8aa3b, v75
	v_exp_f32_e32 v163, v142
	v_rcp_f32_e32 v3, v132
	s_nop 0
	v_mul_f32_e32 v160, 1.0, v3
	v_pk_add_f32 v[162:163], v[162:163], 1.0 op_sel_hi:[1,0]
	v_mul_f32_e32 v3, 0xbfb8aa3b, v82
	v_exp_f32_e32 v166, v3
	v_mul_f32_e32 v142, 0xbfb8aa3b, v83
	v_exp_f32_e32 v167, v142
	v_rcp_f32_e32 v3, v163
	s_nop 0
	v_mul_f32_e32 v133, 1.0, v3
	v_pk_add_f32 v[166:167], v[166:167], 1.0 op_sel_hi:[1,0]
	v_rcp_f32_e32 v3, v162
	s_nop 0
	v_mul_f32_e32 v132, 1.0, v3
	global_store_dwordx4 v[164:165], v[130:133], off
	s_nop 1
	v_rcp_f32_e32 v3, v167
	s_nop 0
	v_mul_f32_e32 v163, 1.0, v3
	v_mul_f32_e32 v130, 0xbfb8aa3b, v62
	v_mul_f32_e32 v131, 0xbfb8aa3b, v63
	v_exp_f32_e32 v130, v130
	v_exp_f32_e32 v131, v131
	v_rcp_f32_e32 v3, v166
	s_nop 0
	v_mul_f32_e32 v162, 1.0, v3
	v_add_u32_e32 v3, 0x80, v2
	global_store_dwordx4 v[164:165], v[160:163], off offset:16
	v_pk_add_f32 v[130:131], v[130:131], 1.0 op_sel_hi:[1,0]
	v_mad_i64_i32 v[164:165], s[8:9], v3, s82, v[148:149]
	v_mul_f32_e32 v3, 0xbfb8aa3b, v70
	v_exp_f32_e32 v132, v3
	v_mul_f32_e32 v133, 0xbfb8aa3b, v71
	v_exp_f32_e32 v133, v133
	v_rcp_f32_e32 v3, v131
	s_nop 0
	v_mul_f32_e32 v131, 1.0, v3
	v_pk_add_f32 v[132:133], v[132:133], 1.0 op_sel_hi:[1,0]
	v_rcp_f32_e32 v3, v130
	s_nop 0
	v_mul_f32_e32 v130, 1.0, v3
	v_rcp_f32_e32 v3, v133
	s_nop 0
	v_mul_f32_e32 v161, 1.0, v3
	v_mul_f32_e32 v142, 0xbfb8aa3b, v58
	v_exp_f32_e32 v162, v142
	v_mul_f32_e32 v142, 0xbfb8aa3b, v59
	v_exp_f32_e32 v163, v142
	v_rcp_f32_e32 v3, v132
	s_nop 0
	v_mul_f32_e32 v160, 1.0, v3
	v_pk_add_f32 v[162:163], v[162:163], 1.0 op_sel_hi:[1,0]
	v_mul_f32_e32 v3, 0xbfb8aa3b, v66
	v_exp_f32_e32 v166, v3
	v_mul_f32_e32 v142, 0xbfb8aa3b, v67
	v_exp_f32_e32 v167, v142
	v_rcp_f32_e32 v3, v163
	s_nop 0
	v_mul_f32_e32 v133, 1.0, v3
	v_pk_add_f32 v[166:167], v[166:167], 1.0 op_sel_hi:[1,0]
	v_rcp_f32_e32 v3, v162
	s_nop 0
	v_mul_f32_e32 v132, 1.0, v3
	global_store_dwordx4 v[164:165], v[130:133], off
	s_nop 1
	v_rcp_f32_e32 v3, v167
	s_nop 0
	v_mul_f32_e32 v163, 1.0, v3
	v_mul_f32_e32 v130, 0xbfb8aa3b, v46
	v_mul_f32_e32 v131, 0xbfb8aa3b, v47
	v_exp_f32_e32 v130, v130
	v_exp_f32_e32 v131, v131
	v_rcp_f32_e32 v3, v166
	s_nop 0
	v_mul_f32_e32 v162, 1.0, v3
	v_add_u32_e32 v3, 0x90, v2
	global_store_dwordx4 v[164:165], v[160:163], off offset:16
	v_pk_add_f32 v[130:131], v[130:131], 1.0 op_sel_hi:[1,0]
	v_mad_i64_i32 v[164:165], s[8:9], v3, s82, v[148:149]
	v_mul_f32_e32 v3, 0xbfb8aa3b, v54
	v_exp_f32_e32 v132, v3
	v_mul_f32_e32 v133, 0xbfb8aa3b, v55
	v_exp_f32_e32 v133, v133
	v_rcp_f32_e32 v3, v131
	s_nop 0
	v_mul_f32_e32 v131, 1.0, v3
	v_pk_add_f32 v[132:133], v[132:133], 1.0 op_sel_hi:[1,0]
	v_rcp_f32_e32 v3, v130
	s_nop 0
	v_mul_f32_e32 v130, 1.0, v3
	v_rcp_f32_e32 v3, v133
	s_nop 0
	v_mul_f32_e32 v161, 1.0, v3
	v_mul_f32_e32 v142, 0xbfb8aa3b, v42
	v_exp_f32_e32 v162, v142
	v_mul_f32_e32 v142, 0xbfb8aa3b, v43
	v_exp_f32_e32 v163, v142
	v_rcp_f32_e32 v3, v132
	s_nop 0
	v_mul_f32_e32 v160, 1.0, v3
	v_pk_add_f32 v[162:163], v[162:163], 1.0 op_sel_hi:[1,0]
	v_mul_f32_e32 v3, 0xbfb8aa3b, v50
	v_exp_f32_e32 v166, v3
	v_mul_f32_e32 v142, 0xbfb8aa3b, v51
	v_exp_f32_e32 v167, v142
	v_rcp_f32_e32 v3, v163
	s_nop 0
	v_mul_f32_e32 v133, 1.0, v3
	v_pk_add_f32 v[166:167], v[166:167], 1.0 op_sel_hi:[1,0]
	v_rcp_f32_e32 v3, v162
	s_nop 0
	v_mul_f32_e32 v132, 1.0, v3
	global_store_dwordx4 v[164:165], v[130:133], off
	s_nop 1
	v_rcp_f32_e32 v3, v167
	s_nop 0
	v_mul_f32_e32 v163, 1.0, v3
	v_mul_f32_e32 v130, 0xbfb8aa3b, v30
	v_mul_f32_e32 v131, 0xbfb8aa3b, v31
	v_exp_f32_e32 v130, v130
	v_exp_f32_e32 v131, v131
	v_rcp_f32_e32 v3, v166
	s_nop 0
	v_mul_f32_e32 v162, 1.0, v3
	v_add_u32_e32 v3, 0xa0, v2
	global_store_dwordx4 v[164:165], v[160:163], off offset:16
	v_pk_add_f32 v[130:131], v[130:131], 1.0 op_sel_hi:[1,0]
	v_mad_i64_i32 v[164:165], s[8:9], v3, s82, v[148:149]
	v_mul_f32_e32 v3, 0xbfb8aa3b, v38
	v_exp_f32_e32 v132, v3
	v_mul_f32_e32 v133, 0xbfb8aa3b, v39
	v_exp_f32_e32 v133, v133
	v_rcp_f32_e32 v3, v131
	s_nop 0
	v_mul_f32_e32 v131, 1.0, v3
	v_pk_add_f32 v[132:133], v[132:133], 1.0 op_sel_hi:[1,0]
	v_rcp_f32_e32 v3, v130
	s_nop 0
	v_mul_f32_e32 v130, 1.0, v3
	v_rcp_f32_e32 v3, v133
	s_nop 0
	v_mul_f32_e32 v161, 1.0, v3
	v_mul_f32_e32 v142, 0xbfb8aa3b, v22
	v_exp_f32_e32 v162, v142
	v_mul_f32_e32 v142, 0xbfb8aa3b, v23
	v_exp_f32_e32 v163, v142
	v_rcp_f32_e32 v3, v132
	s_nop 0
	v_mul_f32_e32 v160, 1.0, v3
	v_pk_add_f32 v[162:163], v[162:163], 1.0 op_sel_hi:[1,0]
	v_mul_f32_e32 v3, 0xbfb8aa3b, v34
	v_exp_f32_e32 v166, v3
	v_mul_f32_e32 v142, 0xbfb8aa3b, v35
	v_exp_f32_e32 v167, v142
	v_rcp_f32_e32 v3, v163
	s_nop 0
	v_mul_f32_e32 v133, 1.0, v3
	v_pk_add_f32 v[166:167], v[166:167], 1.0 op_sel_hi:[1,0]
	v_rcp_f32_e32 v3, v162
	s_nop 0
	v_mul_f32_e32 v132, 1.0, v3
	global_store_dwordx4 v[164:165], v[130:133], off
	s_nop 1
	v_rcp_f32_e32 v3, v167
	s_nop 0
	v_mul_f32_e32 v163, 1.0, v3
	v_mul_f32_e32 v130, 0xbfb8aa3b, v10
	v_mul_f32_e32 v131, 0xbfb8aa3b, v11
	v_exp_f32_e32 v130, v130
	v_exp_f32_e32 v131, v131
	v_rcp_f32_e32 v3, v166
	s_nop 0
	v_mul_f32_e32 v162, 1.0, v3
	v_add_u32_e32 v3, 0xb0, v2
	global_store_dwordx4 v[164:165], v[160:163], off offset:16
	v_pk_add_f32 v[130:131], v[130:131], 1.0 op_sel_hi:[1,0]
	v_mad_i64_i32 v[164:165], s[8:9], v3, s82, v[148:149]
	v_mul_f32_e32 v3, 0xbfb8aa3b, v18
	v_exp_f32_e32 v132, v3
	v_mul_f32_e32 v133, 0xbfb8aa3b, v19
	v_exp_f32_e32 v133, v133
	v_rcp_f32_e32 v3, v131
	s_nop 0
	v_mul_f32_e32 v131, 1.0, v3
	v_pk_add_f32 v[132:133], v[132:133], 1.0 op_sel_hi:[1,0]
	v_rcp_f32_e32 v3, v130
	s_nop 0
	v_mul_f32_e32 v130, 1.0, v3
	v_rcp_f32_e32 v3, v133
	s_nop 0
	v_mul_f32_e32 v161, 1.0, v3
	v_mul_f32_e32 v142, 0xbfb8aa3b, v6
	v_exp_f32_e32 v162, v142
	v_mul_f32_e32 v142, 0xbfb8aa3b, v7
	v_exp_f32_e32 v163, v142
	v_rcp_f32_e32 v3, v132
	s_nop 0
	v_mul_f32_e32 v160, 1.0, v3
	v_pk_add_f32 v[162:163], v[162:163], 1.0 op_sel_hi:[1,0]
	v_mul_f32_e32 v3, 0xbfb8aa3b, v14
	v_exp_f32_e32 v166, v3
	v_mul_f32_e32 v142, 0xbfb8aa3b, v15
	v_exp_f32_e32 v167, v142
	v_rcp_f32_e32 v3, v163
	s_nop 0
	v_mul_f32_e32 v133, 1.0, v3
	v_pk_add_f32 v[166:167], v[166:167], 1.0 op_sel_hi:[1,0]
	v_rcp_f32_e32 v3, v162
	s_nop 0
	v_mul_f32_e32 v132, 1.0, v3
	global_store_dwordx4 v[164:165], v[130:133], off
	s_nop 1
	v_rcp_f32_e32 v3, v167
	s_nop 0
	v_mul_f32_e32 v163, 1.0, v3
	v_rcp_f32_e32 v3, v166
	s_nop 0
	v_mul_f32_e32 v162, 1.0, v3
	global_store_dwordx4 v[164:165], v[160:163], off offset:16
